# DSA prologue: first mask load straight into staging regs (no wait+copy); dilated phase 10: item top waits only for prefetched loads, not for the previous item's stores
# baseline (speedup 1.0000x reference)
; #define LAS __attribute__((address_space(3)))
; template <int D, int STR>
; DI void load_q_frags(Frame& F, bf16x8* qf, const bf16* g0, size_t gstride, LAS unsigned char* buf) {
;     constexpr int CPR = D / 8, NCH = 256 * CPR / NTHR;
;     __syncthreads();
;     int tid_ = F.tid; asm volatile("" : "+v"(tid_));
; #pragma unroll
;     for (int hb = 0; hb < NCH; hb += 4) { u32x4 v[4];
; #pragma unroll
;       for (int k = 0; k < 4; ++k) { const int c = tid_ + (hb + k) * NTHR, r = c / CPR, q = c % CPR; v[k] = *(const u32x4*)(g0 + (size_t)r * gstride + q * 8); }
; #pragma unroll
;       for (int k = 0; k < 4; ++k) { const int c = tid_ + (hb + k) * NTHR, r = c / CPR, q = c % CPR; *(LAS u32x4*)(buf + r * STR + q * 16) = v[k]; } }
;     __syncthreads();
; DI void dsa_unit(Frame& F, int b, int h, int qb) {
;     ...
;       const float k2 = __uint_as_float(((const unsigned*)(F.ws + WS_KMAX))[b * 16 + h]);
;       const float U = sqrtf(qn * k2) * C_D64 * 1.001f + ((const float*)(F.ws + WS_KMAX + 256))[h] + 0.01f;
.LBB0_492:
	s_or_b64 exec, exec, s[12:13]
	s_lshl_b32 s29, s28, 8
	s_add_i32 s12, s29, s35
	s_add_i32 s56, s39, s29
	s_ashr_i32 s13, s12, 31
	s_mul_i32 s8, s12, 0x3600
	v_mov_b32_e32 v14, v146
	s_mul_hi_i32 s5, s12, 0x3600
	s_add_u32 s16, s24, s8
	s_waitcnt lgkmcnt(0)
	s_barrier
	s_addc_u32 s5, s25, s5
	v_add_u32_e32 v10, 0x400, v14
	s_lshl_b32 s8, s4, 6
	s_lshl_b32 s55, s4, 7
	v_ashrrev_i32_e32 v0, 31, v14
	v_ashrrev_i32_e32 v11, 31, v10
	s_add_u32 s16, s16, s55
	v_lshrrev_b32_e32 v0, 29, v0
	v_lshrrev_b32_e32 v11, 29, v11
	s_addc_u32 s5, s5, 0
	v_add_u32_e32 v0, v14, v0
	v_add_u32_e32 v11, v10, v11
	s_add_u32 s16, s16, 0x1800
	v_ashrrev_i32_e32 v16, 3, v0
	v_and_b32_e32 v0, -8, v0
	v_ashrrev_i32_e32 v20, 3, v11
	v_and_b32_e32 v11, -8, v11
	s_addc_u32 s17, s5, 0
	v_sub_u32_e32 v17, v14, v0
	v_sub_u32_e32 v21, v10, v11
	v_mov_b64_e32 v[8:9], s[16:17]
	v_lshlrev_b32_e32 v2, 3, v17
	v_lshlrev_b32_e32 v12, 3, v21
	v_mad_i64_i32 v[0:1], s[16:17], v16, s37, v[8:9]
	v_ashrrev_i32_e32 v3, 31, v2
	v_mad_i64_i32 v[10:11], s[16:17], v20, s37, v[8:9]
	v_ashrrev_i32_e32 v13, 31, v12
	v_lshl_add_u64 v[0:1], v[2:3], 1, v[0:1]
	v_add_u32_e32 v2, 0x200, v14
	v_lshl_add_u64 v[10:11], v[12:13], 1, v[10:11]
	v_add_u32_e32 v12, 0x600, v14
	v_ashrrev_i32_e32 v3, 31, v2
	v_ashrrev_i32_e32 v13, 31, v12
	v_lshrrev_b32_e32 v3, 29, v3
	v_lshrrev_b32_e32 v13, 29, v13
	v_add_u32_e32 v3, v2, v3
	v_add_u32_e32 v13, v12, v13
	v_ashrrev_i32_e32 v18, 3, v3
	v_and_b32_e32 v3, -8, v3
	v_ashrrev_i32_e32 v22, 3, v13
	v_and_b32_e32 v13, -8, v13
	v_sub_u32_e32 v19, v2, v3
	v_sub_u32_e32 v23, v12, v13
	v_lshlrev_b32_e32 v4, 3, v19
	v_lshlrev_b32_e32 v12, 3, v23
	v_mad_i64_i32 v[2:3], s[16:17], v18, s37, v[8:9]
	v_ashrrev_i32_e32 v5, 31, v4
	v_mad_i64_i32 v[8:9], s[16:17], v22, s37, v[8:9]
	v_ashrrev_i32_e32 v13, 31, v12
	v_lshl_add_u64 v[4:5], v[4:5], 1, v[2:3]
	v_lshl_add_u64 v[12:13], v[12:13], 1, v[8:9]
	global_load_dwordx4 v[0:3], v[0:1], off
	s_nop 0
	global_load_dwordx4 v[4:7], v[4:5], off
	s_nop 0
	global_load_dwordx4 v[8:11], v[10:11], off
	s_nop 0
	global_load_dwordx4 v[12:15], v[12:13], off
	s_add_i32 s16, s4, s36
	s_ashr_i32 s17, s16, 31
	s_lshl_b64 s[16:17], s[16:17], 2
	v_mul_lo_u32 v16, v16, s48
	v_lshlrev_b32_e32 v17, 4, v17
	s_add_u32 s16, s42, s16
	v_mov_b32_e32 v24, v144
	v_mul_lo_u32 v18, v18, s48
	v_mul_lo_u32 v20, v20, s48
	v_mul_lo_u32 v22, v22, s48
	v_add3_u32 v16, 0, v16, v17
	v_lshlrev_b32_e32 v17, 4, v19
	v_lshlrev_b32_e32 v19, 4, v21
	v_lshlrev_b32_e32 v21, 4, v23
	s_addc_u32 s17, s43, s17
	v_add3_u32 v17, 0, v18, v17
	v_add3_u32 v18, 0, v20, v19
	v_add3_u32 v19, 0, v22, v21
	s_mov_b32 s5, s9
	s_lshl_b64 s[4:5], s[4:5], 2
	s_add_u32 s4, s44, s4
	s_addc_u32 s5, s45, s5
	v_mov_b32_e32 v141, 0
	s_mov_b32 s58, 0
	s_mov_b32 s59, 0
	s_waitcnt vmcnt(3)
	ds_write_b128 v16, v[0:3]
	s_waitcnt vmcnt(2)
	ds_write_b128 v17, v[4:7]
	s_waitcnt vmcnt(1)
	ds_write_b128 v18, v[8:11]
	s_waitcnt vmcnt(0)
	ds_write_b128 v19, v[12:15]
	s_waitcnt lgkmcnt(0)
	s_barrier
; DI float swap_sum(float m) { auto rr = __builtin_amdgcn_permlane32_swap(__float_as_uint(m), __float_as_uint(m), false, false); return __uint_as_float(rr[0]) + __uint_as_float(rr[1]); }
; DI void dsa_unit(Frame& F, int b, int h, int qb) {
;     ...
;     float S;
;     { float qn = 0.f;
; #pragma unroll
;       for (int st = 0; st < 4; ++st)
; #pragma unroll
;           for (int q = 0; q < 8; ++q) { const float v = __uint_as_float(((unsigned)(unsigned short)qf[st][q]) << 16); qn += v * v; }
;       qn = swap_sum(qn);
;       const float k2 = __uint_as_float(((const unsigned*)(F.ws + WS_KMAX))[b * 16 + h]);
;       const float U = sqrtf(qn * k2) * C_D64 * 1.001f + ((const float*)(F.ws + WS_KMAX + 256))[h] + 0.01f;
;       S = fmaxf(U - 100.f, 0.f); }
;     const bool noshift = __all(S == 0.f);
;     float l = 0.f;
;     const unsigned* mrow = mask + (size_t)(b * SEQ + t) * 128;
;     const int jmax = (t0 + 255) >> 7;
;     RowRegs<64> RK, RV;
;     { const bf16* kg = H0 + (size_t)(b * SEQ) * EVEN_LD + C_KB + h * 64;
;       fetch_rows128<64>(RK, kg, EVEN_LD, F.tid); fetch_rows128<64>(RV, kg + (C_VB - C_KB), EVEN_LD, F.tid); }
;     u32x4 mwn = *(const u32x4*)(mrow);
;     ...
;         if (j < jmax) { const bf16* kg = H0 + (size_t)(b * SEQ + 128 * (j + 1)) * EVEN_LD + C_KB + h * 64;
;             fetch_rows128<64>(RK, kg, EVEN_LD, F.tid); fetch_rows128<64>(RV, kg + (C_VB - C_KB), EVEN_LD, F.tid);
;             mwn = *(const u32x4*)(mrow + 4 * (j + 1)); }
	global_load_dword v2, v107, s[16:17]
	v_and_or_b32 v0, v24, 31, s39
	v_ashrrev_i32_e32 v1, 1, v24
	v_mul_lo_u32 v0, v0, s48
	v_and_b32_e32 v1, -16, v1
	v_add3_u32 v0, 0, v0, v1
	ds_read_b128 v[64:67], v0
	ds_read_b128 v[68:71], v0 offset:32
	ds_read_b128 v[72:75], v0 offset:64
	ds_read_b128 v[76:79], v0 offset:96
	v_mov_b32_e32 v14, v107
	s_waitcnt lgkmcnt(3)
	v_and_b32_e32 v1, 0xffff0000, v64
	v_lshlrev_b32_e32 v0, 16, v64
	v_mul_f32_e32 v1, v1, v1
	v_fmac_f32_e32 v1, v0, v0
	v_lshlrev_b32_e32 v0, 16, v65
	v_fmac_f32_e32 v1, v0, v0
	v_and_b32_e32 v0, 0xffff0000, v65
	v_fmac_f32_e32 v1, v0, v0
	v_lshlrev_b32_e32 v0, 16, v66
	v_fmac_f32_e32 v1, v0, v0
	global_load_dword v0, v107, s[4:5]
	v_and_b32_e32 v3, 0xffff0000, v66
	v_fmac_f32_e32 v1, v3, v3
	v_lshlrev_b32_e32 v3, 16, v67
	v_fmac_f32_e32 v1, v3, v3
	v_and_b32_e32 v3, 0xffff0000, v67
	v_fmac_f32_e32 v1, v3, v3
	s_waitcnt lgkmcnt(2)
	v_lshlrev_b32_e32 v3, 16, v68
	v_fmac_f32_e32 v1, v3, v3
	v_and_b32_e32 v3, 0xffff0000, v68
	v_fmac_f32_e32 v1, v3, v3
	v_lshlrev_b32_e32 v3, 16, v69
	v_fmac_f32_e32 v1, v3, v3
	v_and_b32_e32 v3, 0xffff0000, v69
	v_fmac_f32_e32 v1, v3, v3
	v_lshlrev_b32_e32 v3, 16, v70
	v_fmac_f32_e32 v1, v3, v3
	v_and_b32_e32 v3, 0xffff0000, v70
	v_fmac_f32_e32 v1, v3, v3
	v_lshlrev_b32_e32 v3, 16, v71
	v_fmac_f32_e32 v1, v3, v3
	v_and_b32_e32 v3, 0xffff0000, v71
	v_fmac_f32_e32 v1, v3, v3
	s_waitcnt lgkmcnt(1)
	v_lshlrev_b32_e32 v3, 16, v72
	v_fmac_f32_e32 v1, v3, v3
	v_and_b32_e32 v3, 0xffff0000, v72
	v_fmac_f32_e32 v1, v3, v3
	v_lshlrev_b32_e32 v3, 16, v73
	v_fmac_f32_e32 v1, v3, v3
	v_and_b32_e32 v3, 0xffff0000, v73
	v_fmac_f32_e32 v1, v3, v3
	v_lshlrev_b32_e32 v3, 16, v74
	v_fmac_f32_e32 v1, v3, v3
	v_and_b32_e32 v3, 0xffff0000, v74
	v_fmac_f32_e32 v1, v3, v3
	v_lshlrev_b32_e32 v3, 16, v75
	v_fmac_f32_e32 v1, v3, v3
	v_and_b32_e32 v3, 0xffff0000, v75
	v_fmac_f32_e32 v1, v3, v3
	s_waitcnt lgkmcnt(0)
	v_lshlrev_b32_e32 v3, 16, v76
	v_fmac_f32_e32 v1, v3, v3
	v_and_b32_e32 v3, 0xffff0000, v76
	v_fmac_f32_e32 v1, v3, v3
	v_lshlrev_b32_e32 v3, 16, v77
	v_fmac_f32_e32 v1, v3, v3
	v_and_b32_e32 v3, 0xffff0000, v77
	v_fmac_f32_e32 v1, v3, v3
	v_lshlrev_b32_e32 v3, 16, v78
	v_fmac_f32_e32 v1, v3, v3
	v_and_b32_e32 v3, 0xffff0000, v78
	v_fmac_f32_e32 v1, v3, v3
	v_lshlrev_b32_e32 v3, 16, v79
	v_fmac_f32_e32 v1, v3, v3
	v_and_b32_e32 v3, 0xffff0000, v79
	v_fmac_f32_e32 v1, v3, v3
	v_mov_b32_e32 v3, v1
	s_nop 1
	v_permlane32_swap_b32_e32 v1, v3
	v_add_f32_e32 v1, v1, v3
	v_or_b32_e32 v3, s56, v159
	v_mov_b32_e32 v15, v107
	v_mov_b32_e32 v8, v107
	s_waitcnt vmcnt(1)
	v_mul_f32_e32 v1, v2, v1
	v_mul_f32_e32 v2, 0x4f800000, v1
	v_cmp_gt_f32_e32 vcc, s51, v1
	v_mov_b32_e32 v9, v107
	v_mov_b32_e32 v10, v107
	v_cndmask_b32_e32 v1, v1, v2, vcc
	v_sqrt_f32_e32 v2, v1
	v_mov_b32_e32 v11, v107
	v_mov_b32_e32 v12, v107
	v_mov_b32_e32 v13, v107
	v_add_u32_e32 v4, -1, v2
	v_fma_f32 v5, -v4, v2, v1
	v_cmp_ge_f32_e64 s[4:5], 0, v5
	v_add_u32_e32 v5, 1, v2
	s_nop 0
	v_cndmask_b32_e64 v4, v2, v4, s[4:5]
	v_fma_f32 v2, -v5, v2, v1
	v_cmp_lt_f32_e64 s[4:5], 0, v2
	s_nop 1
	v_cndmask_b32_e64 v2, v4, v5, s[4:5]
	v_mul_f32_e32 v4, 0x37800000, v2
	v_cndmask_b32_e32 v2, v2, v4, vcc
	v_cmp_class_f32_e32 vcc, v1, v134
	s_nop 1
	v_cndmask_b32_e32 v1, v2, v1, vcc
	v_mul_f32_e32 v1, 0x3e38aa3b, v1
	s_waitcnt vmcnt(0)
	v_fmac_f32_e32 v0, 0x3f8020c5, v1
	v_add_f32_e32 v0, 0x3c23d70a, v0
	v_add_f32_e32 v0, 0xc2c80000, v0
	v_max_f32_e32 v138, 0, v0
	v_cmp_eq_f32_e32 vcc, 0, v138
	s_cmp_lg_u64 vcc, exec
	s_cselect_b64 s[16:17], -1, 0
	s_lshl_b32 s54, s28, 1
	s_add_u32 s4, s46, s55
	v_add_u32_e32 v0, s35, v3
	s_addc_u32 s5, s47, 0
	v_ashrrev_i32_e32 v1, 31, v0
	v_lshl_add_u64 v[6:7], s[4:5], 0, v[108:109]
	v_lshlrev_b64 v[0:1], 9, v[0:1]
	v_lshl_add_u64 v[4:5], s[4:5], 0, v[104:105]
	v_lshl_add_u64 v[6:7], v[6:7], 0, v[106:107]
	v_lshl_add_u64 v[2:3], s[6:7], 0, v[0:1]
	v_lshl_add_u64 v[4:5], v[4:5], 0, v[106:107]
	global_load_dwordx4 v[88:91], v[6:7], off
	global_load_dwordx4 v[84:87], v[4:5], off offset:2048
	global_load_dwordx4 v[80:83], v[4:5], off
	global_load_dwordx4 v[96:99], v[2:3], off
	global_load_dwordx4 v[92:95], v[6:7], off offset:2048
	v_lshl_add_u64 v[112:113], s[10:11], 0, v[0:1]
	v_add_lshl_u32 v0, v130, s29, 2
	s_lshl_b32 s57, s28, 10
	v_sub_u32_e32 v139, v119, v0
	v_mov_b32_e32 v0, v107
	v_mov_b32_e32 v1, v107
	v_mov_b32_e32 v2, v107
	v_mov_b32_e32 v3, v107
	v_mov_b32_e32 v4, v107
	v_mov_b32_e32 v5, v107
	v_mov_b32_e32 v6, v107
	v_mov_b32_e32 v7, v107
	v_mov_b64_e32 v[30:31], v[14:15]
	s_mov_b32 s55, 0
	s_or_b32 s56, s56, 31
	s_addk_i32 s57, 0x400
	v_mov_b64_e32 v[28:29], v[12:13]
	v_mov_b64_e32 v[26:27], v[10:11]
	v_mov_b64_e32 v[24:25], v[8:9]
	v_mov_b64_e32 v[22:23], v[6:7]
	v_mov_b64_e32 v[20:21], v[4:5]
	v_mov_b64_e32 v[18:19], v[2:3]
	v_mov_b64_e32 v[16:17], v[0:1]
	s_add_i32 s98, s49, s58
	s_mul_hi_i32 s99, s98, 0x3600
	s_mulk_i32 s98, 0x3600
	s_add_u32 s98, s24, s98
	s_addc_u32 s99, s25, s99
	s_lshl_b32 s100, s8, 1
	s_add_u32 s98, s98, s100
	s_addc_u32 s99, s99, 0
	s_add_u32 s98, s98, 0x2000
	s_addc_u32 s99, s99, 0
	v_lshl_add_u64 v[32:33], s[98:99], 0, v[104:105]
	v_lshl_add_u64 v[32:33], v[32:33], 0, v[106:107]
	v_lshl_add_u64 v[34:35], s[98:99], 0, v[108:109]
	v_lshl_add_u64 v[34:35], v[34:35], 0, v[106:107]
	global_load_dwordx4 v[232:235], v[32:33], off
	global_load_dwordx4 v[236:239], v[32:33], off offset:2048
	global_load_dwordx4 v[240:243], v[34:35], off
	global_load_dwordx4 v[244:247], v[34:35], off offset:2048
	global_load_dwordx4 v[248:251], v[112:113], off

; DI void dil_unit(Frame& F, const DilItem& it, bool has_next, const DilItem& nx, RowRegs<128>& RK, RowRegs<128>& RV) {
;     ...
;     __syncthreads();
;     { const float* bd = (const float*)(F.ws + WS_BIASDIL) + (g * 16 + h) * 160;
;       if (F.tid <= 128) tb[128 - F.tid] = bd[F.tid]; }
.Lqp10_fast0:
	s_waitcnt vmcnt(8)
	s_barrier

; DI void dil_unit(Frame& F, const DilItem& it, bool has_next, const DilItem& nx, RowRegs<128>& RK, RowRegs<128>& RV) {
;     ...
;     __syncthreads();
;     { const float* bd = (const float*)(F.ws + WS_BIASDIL) + (g * 16 + h) * 160;
;       if (F.tid <= 128) tb[128 - F.tid] = bd[F.tid]; }
.LBB0_1090:
	s_and_b32 s98, s47, 15
	s_lshl_b32 s99, s37, 4
	s_or_b32 s98, s98, s99
	s_mulk_i32 s98, 0x280
	v_writelane_b32 v229, s98, 56
	s_and_b32 s60, s6, 15
	v_readlane_b32 s98, v229, 58
	s_nop 0
	s_cmp_lg_u32 s98, 0
	s_cbranch_scc1 .Lqp10_fast0
	s_waitcnt vmcnt(0)
	s_barrier
	s_and_saveexec_b64 s[30:31], s[0:1]
	s_cbranch_execz .LBB0_1092
	s_lshl_b32 s12, s61, 4
	s_or_b32 s12, s12, s60
	s_mulk_i32 s12, 0xa0
	v_lshl_add_u64 v[0:1], s[12:13], 2, v[150:151]
	global_load_dword v0, v[0:1], off
	s_waitcnt vmcnt(0)
	ds_write_b32 v147, v0
